# L1 invalidate of the grid barrier issued right after the arrival counter returns (overlaps the leader's write-back or the poll) instead of before it
# speedup vs baseline: 1.0076x; 1.0076x over previous
.LBB0_58:
	s_or_b64 exec, exec, s[6:7]
	v_writelane_b32 v249, s44, 28
	s_waitcnt lgkmcnt(0)
	s_barrier
	v_writelane_b32 v249, s45, 29
	s_barrier
	s_waitcnt vmcnt(0)
	s_cmp_lt_u32 s8, 64
	v_writelane_b32 v249, s42, 30
	s_cselect_b64 s[74:75], -1, 0
	s_and_b64 vcc, exec, s[74:75]
	v_mbcnt_lo_u32_b32 v12, -1, 0
	v_writelane_b32 v249, s74, 31
	s_barrier
	s_nop 0
	v_writelane_b32 v249, s75, 32
	s_cbranch_vccz .LBB0_106
	v_mbcnt_hi_u32_b32 v0, -1, v12
	v_cmp_eq_u32_e32 vcc, 0, v0
	s_and_saveexec_b64 s[2:3], vcc
	s_cbranch_execz .LBB0_105
	v_readlane_b32 s4, v249, 2
	s_add_i32 s0, 0, 0x22160
	v_readlane_b32 s5, v249, 3
	v_mov_b32_e32 v0, s0
	s_waitcnt vmcnt(0) expcnt(0) lgkmcnt(0)
	ds_read_b32 v2, v0
	s_add_i32 s0, 0, 0x22164
	v_mov_b32_e32 v0, s0
	ds_read_b32 v0, v0
	s_waitcnt lgkmcnt(1)
	v_cmp_eq_u32_e32 vcc, 0, v2
	s_cbranch_vccnz .LBB0_62
	s_lshl_b32 s6, s9, 6
	s_mov_b32 s7, 0
	s_mov_b32 s0, 1
	s_cbranch_execz .LBB0_63
	s_branch .LBB0_76

.LBB0_76:
	s_lshl_b64 s[6:7], s[6:7], 2
	s_add_u32 s1, s4, s6
	s_addc_u32 s0, s5, s7
	v_mov_b32_e32 v1, s1
	v_add_co_u32_e32 v4, vcc, 0x1000, v1
	v_mov_b32_e32 v1, s0
	s_nop 0
	v_addc_co_u32_e32 v5, vcc, 0, v1, vcc
	v_mov_b32_e32 v1, 1
	flat_atomic_add v1, v[4:5], v1 offset:1024 sc0
	v_cvt_f32_u32_e32 v3, v2
	v_sub_u32_e32 v4, 0, v2
	v_rcp_iflag_f32_e32 v3, v3
	s_nop 0
	v_mul_f32_e32 v3, 0x4f7ffffe, v3
	v_cvt_u32_f32_e32 v3, v3
	v_mul_lo_u32 v4, v4, v3
	v_mul_hi_u32 v4, v3, v4
	v_add_u32_e32 v3, v3, v4
	s_waitcnt vmcnt(0) lgkmcnt(0)
	buffer_inv sc1
	v_mul_hi_u32 v3, v1, v3
	v_mul_lo_u32 v5, v3, v2
	v_add_u32_e32 v4, 1, v1
	v_sub_u32_e32 v1, v1, v5
	v_add_u32_e32 v6, 1, v3
	v_cmp_ge_u32_e32 vcc, v1, v2
	v_sub_u32_e32 v5, v1, v2
	s_nop 0
	v_cndmask_b32_e32 v3, v3, v6, vcc
	v_cndmask_b32_e32 v1, v1, v5, vcc
	v_add_u32_e32 v5, 1, v3
	v_cmp_ge_u32_e32 vcc, v1, v2
	s_nop 1
	v_cndmask_b32_e32 v1, v3, v5, vcc
	v_mad_u64_u32 v[2:3], s[6:7], v2, v1, v[2:3]
	v_cmp_ne_u32_e32 vcc, v4, v2
	s_and_saveexec_b64 s[6:7], vcc
	s_xor_b64 s[6:7], exec, s[6:7]
	s_cbranch_execz .LBB0_89
	v_mov_b32_e32 v0, s1
	v_add_co_u32_e32 v2, vcc, 0x2000, v0
	v_mov_b32_e32 v0, s0
	s_nop 0
	v_addc_co_u32_e32 v3, vcc, 0, v0, vcc
	flat_load_dword v0, v[2:3] offset:1024 sc1
	s_add_u32 s14, s1, 0x2400
	s_addc_u32 s15, s0, 0
	s_waitcnt vmcnt(0) lgkmcnt(0)
	v_cmp_eq_u32_e32 vcc, v0, v1
	s_and_saveexec_b64 s[12:13], vcc
	s_cbranch_execz .LBB0_88
	s_mov_b32 s30, 1
	s_mov_b64 s[16:17], 0
	s_branch .LBB0_80

.LBB0_265:
	s_or_b64 exec, exec, s[2:3]
	s_waitcnt vmcnt(0)
	s_mov_b32 s68, s64
	s_and_b64 vcc, exec, s[74:75]
	s_barrier
	s_cbranch_vccz .LBB0_311
	v_cmp_eq_u32_e32 vcc, 0, v208
	s_and_saveexec_b64 s[2:3], vcc
	s_cbranch_execz .LBB0_310
	v_readlane_b32 s4, v249, 2
	v_readlane_b32 s5, v249, 3
	v_mov_b32_e32 v0, s91
	s_waitcnt vmcnt(0) expcnt(0) lgkmcnt(0)
	ds_read_b32 v2, v0
	v_mov_b32_e32 v0, s92
	ds_read_b32 v0, v0
	s_waitcnt lgkmcnt(1)
	v_cmp_ne_u32_e32 vcc, 0, v2
	s_cbranch_vccnz .LBB0_281
	v_readlane_b32 s6, v249, 0
	v_readlane_b32 s7, v249, 1
	s_load_dwordx2 s[0:1], s[6:7], 0x4
	s_lshl_b32 s6, s76, 2
	s_add_u32 s6, s4, s6
	s_addc_u32 s7, s5, 0
	s_add_u32 s10, s4, 0x1000
	s_addc_u32 s11, s5, 0
	s_add_u32 s12, s4, 0x1100
	s_addc_u32 s13, s5, 0
	s_add_u32 s14, s4, 0x1200
	s_addc_u32 s15, s5, 0
	s_waitcnt lgkmcnt(0)
	s_mul_i32 s0, s0, s60
	s_add_u32 s16, s4, 0x1300
	s_mul_i32 s0, s0, s1
	s_addc_u32 s17, s5, 0
	s_mov_b32 s1, 1
	s_mov_b64 s[18:19], 0
	s_branch .LBB0_271

.LBB0_281:
	s_lshl_b32 s0, s76, 2
	s_add_u32 s1, s4, s0
	s_addc_u32 s0, s5, 0
	v_mov_b32_e32 v1, s1
	v_add_co_u32_e32 v4, vcc, 0x1000, v1
	v_mov_b32_e32 v1, s0
	s_nop 0
	v_addc_co_u32_e32 v5, vcc, 0, v1, vcc
	flat_atomic_add v1, v[4:5], v195 offset:1024 sc0
	v_cvt_f32_u32_e32 v3, v2
	v_sub_u32_e32 v4, 0, v2
	v_rcp_iflag_f32_e32 v3, v3
	s_nop 0
	v_mul_f32_e32 v3, 0x4f7ffffe, v3
	v_cvt_u32_f32_e32 v3, v3
	v_mul_lo_u32 v4, v4, v3
	v_mul_hi_u32 v4, v3, v4
	v_add_u32_e32 v3, v3, v4
	s_waitcnt vmcnt(0) lgkmcnt(0)
	buffer_inv sc1
	v_mul_hi_u32 v3, v1, v3
	v_mul_lo_u32 v5, v3, v2
	v_add_u32_e32 v4, 1, v1
	v_sub_u32_e32 v1, v1, v5
	v_add_u32_e32 v6, 1, v3
	v_sub_u32_e32 v5, v1, v2
	v_cmp_ge_u32_e32 vcc, v1, v2
	s_nop 1
	v_cndmask_b32_e32 v3, v3, v6, vcc
	v_cndmask_b32_e32 v1, v1, v5, vcc
	v_add_u32_e32 v5, 1, v3
	v_cmp_ge_u32_e32 vcc, v1, v2
	s_nop 1
	v_cndmask_b32_e32 v1, v3, v5, vcc
	v_mad_u64_u32 v[2:3], s[6:7], v2, v1, v[2:3]
	v_cmp_ne_u32_e32 vcc, v4, v2
	s_and_saveexec_b64 s[6:7], vcc
	s_xor_b64 s[6:7], exec, s[6:7]
	s_cbranch_execz .LBB0_294
	v_mov_b32_e32 v0, s1
	v_add_co_u32_e32 v2, vcc, 0x2000, v0
	v_mov_b32_e32 v0, s0
	s_nop 0
	v_addc_co_u32_e32 v3, vcc, 0, v0, vcc
	flat_load_dword v0, v[2:3] offset:1024 sc1
	s_add_u32 s12, s1, 0x2400
	s_addc_u32 s13, s0, 0
	s_waitcnt vmcnt(0) lgkmcnt(0)
	v_cmp_eq_u32_e32 vcc, v0, v1
	s_and_saveexec_b64 s[10:11], vcc
	s_cbranch_execz .LBB0_293
	s_mov_b32 s30, 1
	s_mov_b64 s[14:15], 0
	s_branch .LBB0_285

.LBB0_342:
	s_waitcnt vmcnt(0)
	s_andn2_b64 vcc, exec, s[74:75]
	s_waitcnt lgkmcnt(0)
	s_barrier
	s_cbranch_vccnz .LBB0_388
	v_cmp_eq_u32_e32 vcc, 0, v208
	s_and_saveexec_b64 s[2:3], vcc
	s_cbranch_execz .LBB0_387
	v_readlane_b32 s4, v249, 2
	v_readlane_b32 s5, v249, 3
	v_mov_b32_e32 v0, s91
	s_waitcnt vmcnt(0) expcnt(0) lgkmcnt(0)
	ds_read_b32 v2, v0
	v_mov_b32_e32 v0, s92
	ds_read_b32 v0, v0
	s_waitcnt lgkmcnt(1)
	v_cmp_ne_u32_e32 vcc, 0, v2
	s_cbranch_vccnz .LBB0_358
	v_readlane_b32 s6, v249, 0
	v_readlane_b32 s7, v249, 1
	s_load_dwordx2 s[0:1], s[6:7], 0x4
	s_lshl_b32 s6, s76, 2
	s_add_u32 s6, s4, s6
	s_addc_u32 s7, s5, 0
	s_add_u32 s10, s4, 0x1000
	s_addc_u32 s11, s5, 0
	s_add_u32 s12, s4, 0x1100
	s_addc_u32 s13, s5, 0
	s_add_u32 s14, s4, 0x1200
	s_addc_u32 s15, s5, 0
	s_waitcnt lgkmcnt(0)
	s_mul_i32 s0, s0, s60
	s_add_u32 s16, s4, 0x1300
	s_mul_i32 s0, s0, s1
	s_addc_u32 s17, s5, 0
	s_mov_b32 s1, 1
	s_mov_b64 s[18:19], 0
	s_branch .LBB0_348

.LBB0_358:
	s_lshl_b32 s0, s76, 2
	s_add_u32 s1, s4, s0
	s_addc_u32 s0, s5, 0
	v_mov_b32_e32 v1, s1
	v_add_co_u32_e32 v4, vcc, 0x1000, v1
	v_mov_b32_e32 v1, s0
	s_nop 0
	v_addc_co_u32_e32 v5, vcc, 0, v1, vcc
	flat_atomic_add v1, v[4:5], v195 offset:1024 sc0
	v_cvt_f32_u32_e32 v3, v2
	v_sub_u32_e32 v4, 0, v2
	v_rcp_iflag_f32_e32 v3, v3
	s_nop 0
	v_mul_f32_e32 v3, 0x4f7ffffe, v3
	v_cvt_u32_f32_e32 v3, v3
	v_mul_lo_u32 v4, v4, v3
	v_mul_hi_u32 v4, v3, v4
	v_add_u32_e32 v3, v3, v4
	s_waitcnt vmcnt(0) lgkmcnt(0)
	buffer_inv sc1
	v_mul_hi_u32 v3, v1, v3
	v_mul_lo_u32 v5, v3, v2
	v_add_u32_e32 v4, 1, v1
	v_sub_u32_e32 v1, v1, v5
	v_add_u32_e32 v6, 1, v3
	v_sub_u32_e32 v5, v1, v2
	v_cmp_ge_u32_e32 vcc, v1, v2
	s_nop 1
	v_cndmask_b32_e32 v3, v3, v6, vcc
	v_cndmask_b32_e32 v1, v1, v5, vcc
	v_add_u32_e32 v5, 1, v3
	v_cmp_ge_u32_e32 vcc, v1, v2
	s_nop 1
	v_cndmask_b32_e32 v1, v3, v5, vcc
	v_mad_u64_u32 v[2:3], s[6:7], v2, v1, v[2:3]
	v_cmp_ne_u32_e32 vcc, v4, v2
	s_and_saveexec_b64 s[6:7], vcc
	s_xor_b64 s[6:7], exec, s[6:7]
	s_cbranch_execz .LBB0_371
	v_mov_b32_e32 v0, s1
	v_add_co_u32_e32 v2, vcc, 0x2000, v0
	v_mov_b32_e32 v0, s0
	s_nop 0
	v_addc_co_u32_e32 v3, vcc, 0, v0, vcc
	flat_load_dword v0, v[2:3] offset:1024 sc1
	s_add_u32 s12, s1, 0x2400
	s_addc_u32 s13, s0, 0
	s_waitcnt vmcnt(0) lgkmcnt(0)
	v_cmp_eq_u32_e32 vcc, v0, v1
	s_and_saveexec_b64 s[10:11], vcc
	s_cbranch_execz .LBB0_370
	s_mov_b32 s8, 1
	s_mov_b64 s[14:15], 0
	s_branch .LBB0_362

.LBB0_439:
	s_waitcnt vmcnt(0)
	s_and_b64 vcc, exec, s[74:75]
	s_barrier
	s_cbranch_vccz .LBB0_485
	v_cmp_eq_u32_e32 vcc, 0, v208
	s_and_saveexec_b64 s[2:3], vcc
	s_cbranch_execz .LBB0_484
	v_readlane_b32 s4, v249, 2
	v_readlane_b32 s5, v249, 3
	v_mov_b32_e32 v0, s91
	s_waitcnt vmcnt(0) expcnt(0) lgkmcnt(0)
	ds_read_b32 v2, v0
	v_mov_b32_e32 v0, s92
	ds_read_b32 v0, v0
	s_waitcnt lgkmcnt(1)
	v_cmp_ne_u32_e32 vcc, 0, v2
	s_cbranch_vccnz .LBB0_455
	v_readlane_b32 s6, v249, 0
	v_readlane_b32 s7, v249, 1
	s_load_dwordx2 s[0:1], s[6:7], 0x4
	s_lshl_b32 s6, s76, 2
	s_add_u32 s6, s4, s6
	s_addc_u32 s7, s5, 0
	s_add_u32 s10, s4, 0x1000
	s_addc_u32 s11, s5, 0
	s_add_u32 s12, s4, 0x1100
	s_addc_u32 s13, s5, 0
	s_add_u32 s14, s4, 0x1200
	s_addc_u32 s15, s5, 0
	s_waitcnt lgkmcnt(0)
	s_mul_i32 s0, s0, s60
	s_add_u32 s16, s4, 0x1300
	s_mul_i32 s0, s0, s1
	s_addc_u32 s17, s5, 0
	s_mov_b32 s1, 1
	s_mov_b64 s[18:19], 0
	s_branch .LBB0_445

.LBB0_503:
	s_waitcnt vmcnt(0)
	s_andn2_b64 vcc, exec, s[74:75]
	s_waitcnt lgkmcnt(0)
	s_barrier
	s_cbranch_vccnz .LBB0_549
	v_cmp_eq_u32_e32 vcc, 0, v208
	s_and_saveexec_b64 s[2:3], vcc
	s_cbranch_execz .LBB0_548
	v_readlane_b32 s4, v249, 2
	v_readlane_b32 s5, v249, 3
	v_mov_b32_e32 v0, s91
	s_waitcnt vmcnt(0) expcnt(0) lgkmcnt(0)
	ds_read_b32 v2, v0
	v_mov_b32_e32 v0, s92
	ds_read_b32 v0, v0
	s_waitcnt lgkmcnt(1)
	v_cmp_ne_u32_e32 vcc, 0, v2
	s_cbranch_vccnz .LBB0_519
	v_readlane_b32 s6, v249, 0
	v_readlane_b32 s7, v249, 1
	s_load_dwordx2 s[0:1], s[6:7], 0x4
	s_lshl_b32 s6, s76, 2
	s_add_u32 s6, s4, s6
	s_addc_u32 s7, s5, 0
	s_add_u32 s10, s4, 0x1000
	s_addc_u32 s11, s5, 0
	s_add_u32 s12, s4, 0x1100
	s_addc_u32 s13, s5, 0
	s_add_u32 s16, s4, 0x1200
	s_addc_u32 s17, s5, 0
	s_waitcnt lgkmcnt(0)
	s_mul_i32 s0, s0, s60
	s_add_u32 s18, s4, 0x1300
	s_mul_i32 s0, s0, s1
	s_addc_u32 s19, s5, 0
	s_mov_b32 s1, 1
	s_mov_b64 s[20:21], 0
	s_branch .LBB0_509

.LBB0_519:
	s_lshl_b32 s0, s76, 2
	s_add_u32 s1, s4, s0
	s_addc_u32 s0, s5, 0
	v_mov_b32_e32 v1, s1
	v_add_co_u32_e32 v4, vcc, 0x1000, v1
	v_mov_b32_e32 v1, s0
	s_nop 0
	v_addc_co_u32_e32 v5, vcc, 0, v1, vcc
	flat_atomic_add v3, v[4:5], v195 offset:1024 sc0
	v_cvt_f32_u32_e32 v1, v2
	v_sub_u32_e32 v4, 0, v2
	v_rcp_iflag_f32_e32 v1, v1
	s_nop 0
	v_mul_f32_e32 v1, 0x4f7ffffe, v1
	v_cvt_u32_f32_e32 v1, v1
	v_mul_lo_u32 v4, v4, v1
	v_mul_hi_u32 v4, v1, v4
	v_add_u32_e32 v1, v1, v4
	s_waitcnt vmcnt(0) lgkmcnt(0)
	buffer_inv sc1
	v_mul_hi_u32 v1, v3, v1
	v_mul_lo_u32 v4, v1, v2
	v_sub_u32_e32 v4, v3, v4
	v_cmp_ge_u32_e32 vcc, v4, v2
	v_add_u32_e32 v5, 1, v1
	s_nop 0
	v_cndmask_b32_e32 v1, v1, v5, vcc
	v_sub_u32_e32 v5, v4, v2
	v_cndmask_b32_e32 v4, v4, v5, vcc
	v_cmp_ge_u32_e32 vcc, v4, v2
	v_add_u32_e32 v4, 1, v1
	s_nop 0
	v_cndmask_b32_e32 v1, v1, v4, vcc
	v_add_u32_e32 v4, 1, v3
	v_mad_u64_u32 v[2:3], s[6:7], v2, v1, v[2:3]
	v_cmp_ne_u32_e32 vcc, v4, v2
	s_and_saveexec_b64 s[6:7], vcc
	s_xor_b64 s[6:7], exec, s[6:7]
	s_cbranch_execz .LBB0_532
	v_mov_b32_e32 v0, s1
	v_add_co_u32_e32 v2, vcc, 0x2000, v0
	v_mov_b32_e32 v0, s0
	s_nop 0
	v_addc_co_u32_e32 v3, vcc, 0, v0, vcc
	flat_load_dword v0, v[2:3] offset:1024 sc1
	s_add_u32 s12, s1, 0x2400
	s_addc_u32 s13, s0, 0
	s_waitcnt vmcnt(0) lgkmcnt(0)
	v_cmp_eq_u32_e32 vcc, v0, v1
	s_and_saveexec_b64 s[10:11], vcc
	s_cbranch_execz .LBB0_531
	s_mov_b32 s8, 1
	s_mov_b64 s[16:17], 0
	s_branch .LBB0_523

.LBB0_860:
	s_waitcnt vmcnt(0)
	v_cmp_eq_u32_e32 vcc, 0, v208
	s_and_b64 s[0:1], s[74:75], vcc
	s_waitcnt vmcnt(0) lgkmcnt(0)
	s_barrier
	s_and_saveexec_b64 s[2:3], s[0:1]
	s_cbranch_execz .LBB0_904
	v_readlane_b32 s4, v249, 2
	v_readlane_b32 s5, v249, 3
	v_mov_b32_e32 v0, s91
	s_waitcnt vmcnt(0) expcnt(0) lgkmcnt(0)
	ds_read_b32 v2, v0
	v_mov_b32_e32 v0, s92
	ds_read_b32 v0, v0
	s_waitcnt lgkmcnt(1)
	v_cmp_ne_u32_e32 vcc, 0, v2
	s_cbranch_vccnz .LBB0_875
	v_readlane_b32 s6, v249, 0
	v_readlane_b32 s7, v249, 1
	s_load_dwordx2 s[0:1], s[6:7], 0x4
	s_lshl_b32 s6, s76, 2
	s_add_u32 s6, s4, s6
	s_addc_u32 s7, s5, 0
	s_add_u32 s10, s4, 0x1000
	s_addc_u32 s11, s5, 0
	s_add_u32 s12, s4, 0x1100
	s_addc_u32 s13, s5, 0
	s_add_u32 s14, s4, 0x1200
	s_addc_u32 s15, s5, 0
	s_waitcnt lgkmcnt(0)
	s_mul_i32 s0, s0, s60
	s_add_u32 s16, s4, 0x1300
	s_mul_i32 s0, s0, s1
	s_addc_u32 s17, s5, 0
	s_mov_b32 s1, 1
	s_mov_b64 s[18:19], 0
	s_branch .LBB0_865

.LBB0_875:
	s_lshl_b32 s0, s76, 2
	s_add_u32 s1, s4, s0
	s_addc_u32 s0, s5, 0
	v_mov_b32_e32 v1, s1
	v_add_co_u32_e32 v4, vcc, 0x1000, v1
	v_mov_b32_e32 v1, s0
	s_nop 0
	v_addc_co_u32_e32 v5, vcc, 0, v1, vcc
	flat_atomic_add v3, v[4:5], v195 offset:1024 sc0
	v_cvt_f32_u32_e32 v1, v2
	v_sub_u32_e32 v4, 0, v2
	v_rcp_iflag_f32_e32 v1, v1
	s_nop 0
	v_mul_f32_e32 v1, 0x4f7ffffe, v1
	v_cvt_u32_f32_e32 v1, v1
	v_mul_lo_u32 v4, v4, v1
	v_mul_hi_u32 v4, v1, v4
	v_add_u32_e32 v1, v1, v4
	s_waitcnt vmcnt(0) lgkmcnt(0)
	buffer_inv sc1
	v_mul_hi_u32 v1, v3, v1
	v_mul_lo_u32 v4, v1, v2
	v_sub_u32_e32 v4, v3, v4
	v_cmp_ge_u32_e32 vcc, v4, v2
	v_add_u32_e32 v5, 1, v1
	s_nop 0
	v_cndmask_b32_e32 v1, v1, v5, vcc
	v_sub_u32_e32 v5, v4, v2
	v_cndmask_b32_e32 v4, v4, v5, vcc
	v_cmp_ge_u32_e32 vcc, v4, v2
	v_add_u32_e32 v4, 1, v1
	s_nop 0
	v_cndmask_b32_e32 v1, v1, v4, vcc
	v_add_u32_e32 v4, 1, v3
	v_mad_u64_u32 v[2:3], s[6:7], v2, v1, v[2:3]
	v_cmp_ne_u32_e32 vcc, v4, v2
	s_and_saveexec_b64 s[6:7], vcc
	s_xor_b64 s[6:7], exec, s[6:7]
	s_cbranch_execz .LBB0_888
	v_mov_b32_e32 v0, s1
	v_add_co_u32_e32 v2, vcc, 0x2000, v0
	v_mov_b32_e32 v0, s0
	s_nop 0
	v_addc_co_u32_e32 v3, vcc, 0, v0, vcc
	flat_load_dword v0, v[2:3] offset:1024 sc1
	s_add_u32 s12, s1, 0x2400
	s_addc_u32 s13, s0, 0
	s_waitcnt vmcnt(0) lgkmcnt(0)
	v_cmp_eq_u32_e32 vcc, v0, v1
	s_and_saveexec_b64 s[10:11], vcc
	s_cbranch_execz .LBB0_887
	s_mov_b32 s8, 1
	s_mov_b64 s[14:15], 0
	s_branch .LBB0_879

.LBB0_932:
	s_or_b64 exec, exec, s[10:11]
	s_waitcnt vmcnt(0)
	s_mov_b32 s71, s69
	s_and_b64 vcc, exec, s[74:75]
	s_barrier
	s_cbranch_vccz .LBB0_978
	v_cmp_eq_u32_e32 vcc, 0, v208
	s_and_saveexec_b64 s[2:3], vcc
	s_cbranch_execz .LBB0_977
	v_readlane_b32 s4, v249, 2
	v_readlane_b32 s5, v249, 3
	v_mov_b32_e32 v0, s91
	s_waitcnt vmcnt(0) expcnt(0) lgkmcnt(0)
	ds_read_b32 v2, v0
	v_mov_b32_e32 v0, s92
	ds_read_b32 v0, v0
	s_waitcnt lgkmcnt(1)
	v_cmp_ne_u32_e32 vcc, 0, v2
	s_cbranch_vccnz .LBB0_948
	v_readlane_b32 s10, v249, 0
	v_readlane_b32 s11, v249, 1
	s_load_dwordx2 s[14:15], s[10:11], 0x4
	s_lshl_b32 s1, s76, 2
	s_add_u32 s10, s4, s1
	s_addc_u32 s11, s5, 0
	s_add_u32 s12, s4, 0x1000
	s_addc_u32 s13, s5, 0
	s_waitcnt lgkmcnt(0)
	s_mul_i32 s1, s14, s60
	s_add_u32 s14, s4, 0x1100
	s_mul_i32 s1, s1, s15
	s_addc_u32 s15, s5, 0
	s_add_u32 s16, s4, 0x1200
	s_addc_u32 s17, s5, 0
	s_add_u32 s18, s4, 0x1300
	s_addc_u32 s19, s5, 0
	s_mov_b32 s9, 1
	s_mov_b64 s[20:21], 0
	s_branch .LBB0_938

.LBB0_948:
	s_lshl_b32 s1, s76, 2
	s_add_u32 s9, s4, s1
	s_addc_u32 s1, s5, 0
	v_mov_b32_e32 v1, s9
	v_add_co_u32_e32 v4, vcc, 0x1000, v1
	v_mov_b32_e32 v1, s1
	s_nop 0
	v_addc_co_u32_e32 v5, vcc, 0, v1, vcc
	flat_atomic_add v1, v[4:5], v195 offset:1024 sc0
	v_cvt_f32_u32_e32 v3, v2
	v_sub_u32_e32 v4, 0, v2
	v_rcp_iflag_f32_e32 v3, v3
	s_nop 0
	v_mul_f32_e32 v3, 0x4f7ffffe, v3
	v_cvt_u32_f32_e32 v3, v3
	v_mul_lo_u32 v4, v4, v3
	v_mul_hi_u32 v4, v3, v4
	v_add_u32_e32 v3, v3, v4
	s_waitcnt vmcnt(0) lgkmcnt(0)
	buffer_inv sc1
	v_mul_hi_u32 v3, v1, v3
	v_mul_lo_u32 v5, v3, v2
	v_add_u32_e32 v4, 1, v1
	v_sub_u32_e32 v1, v1, v5
	v_add_u32_e32 v6, 1, v3
	v_sub_u32_e32 v5, v1, v2
	v_cmp_ge_u32_e32 vcc, v1, v2
	s_nop 1
	v_cndmask_b32_e32 v3, v3, v6, vcc
	v_cndmask_b32_e32 v1, v1, v5, vcc
	v_add_u32_e32 v5, 1, v3
	v_cmp_ge_u32_e32 vcc, v1, v2
	s_nop 1
	v_cndmask_b32_e32 v1, v3, v5, vcc
	v_mad_u64_u32 v[2:3], s[10:11], v2, v1, v[2:3]
	v_cmp_ne_u32_e32 vcc, v4, v2
	s_and_saveexec_b64 s[10:11], vcc
	s_xor_b64 s[10:11], exec, s[10:11]
	s_cbranch_execz .LBB0_961
	v_mov_b32_e32 v0, s9
	v_add_co_u32_e32 v2, vcc, 0x2000, v0
	v_mov_b32_e32 v0, s1
	s_nop 0
	v_addc_co_u32_e32 v3, vcc, 0, v0, vcc
	flat_load_dword v0, v[2:3] offset:1024 sc1
	s_add_u32 s14, s9, 0x2400
	s_addc_u32 s15, s1, 0
	s_waitcnt vmcnt(0) lgkmcnt(0)
	v_cmp_eq_u32_e32 vcc, v0, v1
	s_and_saveexec_b64 s[12:13], vcc
	s_cbranch_execz .LBB0_960
	s_mov_b32 s29, 1
	s_mov_b64 s[16:17], 0
	s_branch .LBB0_952

.LBB0_983:
	s_or_b64 exec, exec, s[4:5]
	s_waitcnt vmcnt(0)
	v_cndmask_b32_e64 v0, 0, 1, s[74:75]
	v_cmp_ne_u32_e64 s[2:3], 1, v0
	s_andn2_b64 vcc, exec, s[74:75]
	s_movk_i32 s29, 0x110
	s_movk_i32 s42, 0x88
	v_readlane_b32 s43, v249, 15
	s_movk_i32 s44, 0x60
	s_movk_i32 s45, 0x6000
	s_mov_b64 s[46:47], 0x12f00000
	s_mov_b64 s[50:51], 0x1af00400
	s_mov_b32 s56, s34
	s_mov_b32 s62, s80
	s_mov_b32 s69, s71
	s_barrier
	s_cbranch_vccnz .LBB0_1029
	v_cmp_eq_u32_e32 vcc, 0, v208
	s_and_saveexec_b64 s[4:5], vcc
	s_cbranch_execz .LBB0_1028
	v_readlane_b32 s10, v249, 2
	v_readlane_b32 s11, v249, 3
	v_mov_b32_e32 v0, s91
	s_waitcnt vmcnt(0) expcnt(0) lgkmcnt(0)
	ds_read_b32 v2, v0
	v_mov_b32_e32 v0, s92
	ds_read_b32 v0, v0
	s_waitcnt lgkmcnt(1)
	v_cmp_ne_u32_e32 vcc, 0, v2
	s_cbranch_vccnz .LBB0_999
	v_readlane_b32 s8, v249, 0
	v_readlane_b32 s9, v249, 1
	s_load_dwordx2 s[0:1], s[8:9], 0x4
	s_lshl_b32 s8, s76, 2
	s_add_u32 s12, s10, s8
	s_addc_u32 s13, s11, 0
	s_add_u32 s14, s10, 0x1000
	s_addc_u32 s15, s11, 0
	s_add_u32 s16, s10, 0x1100
	s_addc_u32 s17, s11, 0
	s_add_u32 s18, s10, 0x1200
	s_addc_u32 s19, s11, 0
	s_waitcnt lgkmcnt(0)
	s_mul_i32 s0, s0, s60
	s_add_u32 s20, s10, 0x1300
	s_mul_i32 s0, s0, s1
	s_addc_u32 s21, s11, 0
	s_mov_b32 s1, 1
	s_mov_b64 s[22:23], 0
	s_branch .LBB0_989

.LBB0_999:
	s_lshl_b32 s0, s76, 2
	s_add_u32 s1, s10, s0
	s_addc_u32 s0, s11, 0
	v_mov_b32_e32 v1, s1
	v_add_co_u32_e32 v4, vcc, 0x1000, v1
	v_mov_b32_e32 v1, s0
	s_nop 0
	v_addc_co_u32_e32 v5, vcc, 0, v1, vcc
	flat_atomic_add v1, v[4:5], v195 offset:1024 sc0
	v_cvt_f32_u32_e32 v3, v2
	v_sub_u32_e32 v4, 0, v2
	v_rcp_iflag_f32_e32 v3, v3
	s_nop 0
	v_mul_f32_e32 v3, 0x4f7ffffe, v3
	v_cvt_u32_f32_e32 v3, v3
	v_mul_lo_u32 v4, v4, v3
	v_mul_hi_u32 v4, v3, v4
	v_add_u32_e32 v3, v3, v4
	s_waitcnt vmcnt(0) lgkmcnt(0)
	buffer_inv sc1
	v_mul_hi_u32 v3, v1, v3
	v_mul_lo_u32 v5, v3, v2
	v_add_u32_e32 v4, 1, v1
	v_sub_u32_e32 v1, v1, v5
	v_add_u32_e32 v6, 1, v3
	v_sub_u32_e32 v5, v1, v2
	v_cmp_ge_u32_e32 vcc, v1, v2
	s_nop 1
	v_cndmask_b32_e32 v3, v3, v6, vcc
	v_cndmask_b32_e32 v1, v1, v5, vcc
	v_add_u32_e32 v5, 1, v3
	v_cmp_ge_u32_e32 vcc, v1, v2
	s_nop 1
	v_cndmask_b32_e32 v1, v3, v5, vcc
	v_mad_u64_u32 v[2:3], s[8:9], v2, v1, v[2:3]
	v_cmp_ne_u32_e32 vcc, v4, v2
	s_and_saveexec_b64 s[8:9], vcc
	s_xor_b64 s[12:13], exec, s[8:9]
	s_cbranch_execz .LBB0_1012
	v_mov_b32_e32 v0, s1
	v_add_co_u32_e32 v2, vcc, 0x2000, v0
	v_mov_b32_e32 v0, s0
	s_nop 0
	v_addc_co_u32_e32 v3, vcc, 0, v0, vcc
	flat_load_dword v0, v[2:3] offset:1024 sc1
	s_add_u32 s16, s1, 0x2400
	s_addc_u32 s17, s0, 0
	s_waitcnt vmcnt(0) lgkmcnt(0)
	v_cmp_eq_u32_e32 vcc, v0, v1
	s_and_saveexec_b64 s[14:15], vcc
	s_cbranch_execz .LBB0_1011
	s_mov_b32 s8, 1
	s_mov_b64 s[18:19], 0
	s_branch .LBB0_1003

.LBB0_1044:
	v_readlane_b32 s4, v249, 2
	v_readlane_b32 s5, v249, 3
	v_mov_b32_e32 v0, s91
	s_waitcnt vmcnt(0) expcnt(0) lgkmcnt(0)
	ds_read_b32 v2, v0
	v_mov_b32_e32 v0, s92
	ds_read_b32 v0, v0
	s_waitcnt lgkmcnt(1)
	v_cmp_ne_u32_e32 vcc, 0, v2
	s_cbranch_vccnz .LBB0_1058
	v_readlane_b32 s6, v249, 0
	v_readlane_b32 s7, v249, 1
	s_load_dwordx2 s[0:1], s[6:7], 0x4
	s_lshl_b32 s6, s76, 2
	s_add_u32 s6, s4, s6
	s_addc_u32 s7, s5, 0
	s_add_u32 s10, s4, 0x1000
	s_addc_u32 s11, s5, 0
	s_add_u32 s12, s4, 0x1100
	s_addc_u32 s13, s5, 0
	s_add_u32 s14, s4, 0x1200
	s_addc_u32 s15, s5, 0
	s_waitcnt lgkmcnt(0)
	s_mul_i32 s0, s0, s60
	s_add_u32 s16, s4, 0x1300
	s_mul_i32 s0, s0, s1
	s_addc_u32 s17, s5, 0
	s_mov_b32 s1, 1
	s_mov_b64 s[18:19], 0
	s_branch .LBB0_1048
